# P3 chain rewrite + fused diff-attention loop with 2-deep K/V prefetch and bank-conflict-free K fragment layout in LDS
# speedup vs baseline: 1.0041x; 1.0041x over previous
;     template <bool BG = false>
;     __device__ __forceinline__ void run(LAS unsigned char* lds, f32x16 (&O)[NCOMP][NBLK], BgConv* bg = nullptr) const {
;     ...
;         auto body = [&](const int t, auto moret, auto bgt) {
;             constexpr bool more = decltype(moret)::value, BGI = decltype(bgt)::value;
;             if (more) tile_load(kreg, K + (size_t)(64 * (t + 1)) * ldk, ldk, tid);
;             f32x16 st;
; #pragma unroll
;             for (int i = 0; i < 16; ++i) st[i] = 0.f;
;             if (DH == 128) {
;                 bf16x8 kfa[KS];
; #pragma unroll
;                 for (int s = 0; s < KS; ++s) kfa[s] = *(const LAS bf16x8*)(kbuf + ((32 * kh + r) * NCOMP + compA) * KST + (16 * s + 8 * h) * 2);
;                 asm volatile("" ::: "memory");
;                 tile_store_raw(vreg, vbuf, tid);
; #pragma unroll
;                 for (int s = 0; s < KS; ++s) st = MFMA32(kfa[s], qf[s], st);
;             } else {
;             tile_store_raw(vreg, vbuf, tid);
; #pragma unroll
;             for (int s = 0; s < KS; ++s) { const bf16x8 kf = *(const LAS bf16x8*)(kbuf + ((32 * kh + r) * NCOMP + compA) * KST + (16 * s + 8 * h) * 2); st = MFMA32(kf, qf[s], st);
;                 if ((s & 3) == 3) asm volatile("" ::: "memory"); }
;             }
;             float pe[16];
; #pragma unroll
;             for (int i = 0; i < 16; ++i) { pe[i] = fexp2(st[i] - m2); lsum += pe[i]; }
; #pragma unroll
;             for (int g = 0; g < 4; ++g) { u32x2 w; w.x = pk2(pe[4 * g], pe[4 * g + 1]); w.y = pk2(pe[4 * g + 2], pe[4 * g + 3]);
;                 *(LAS u32x2*)(pbuf + ((compA * NRB + rbA) * 32 + r) * PST + (32 * kh + 8 * g + 4 * h) * 2) = w; }
;             __syncthreads();
;             if (more) tile_load(vreg, V + (size_t)(64 * (t + 1)) * ldv, ldv, tid);
; #pragma unroll
;             for (int s = 0; s < 4; ++s) {
;                 bf16x8 pf[NCOMP];
; #pragma unroll
;                 for (int c = 0; c < NCOMP; ++c) pf[c] = *(const LAS bf16x8*)(pbuf + ((c * NRB + rbB) * 32 + r) * PST + (16 * s + 8 * h) * 2);
; #pragma unroll
;                 for (int b = 0; b < NBLK; ++b) {
;                     const bf16x8 vf = trfrag(vbuf + (16 * s + 8 * h + q4) * VST + (DVW * dvp + 32 * b + 16 * b16 + 4 * p4) * 2, 4 * VST);
; #pragma unroll
;                     for (int c = 0; c < NCOMP; ++c) O[c][b] = MFMA32(pf[c], vf, O[c][b]);
;                 }
.LBB0_740:
	s_waitcnt vmcnt(0)
	v_mov_b64_e32 v[160:161], v[152:153]
	v_mov_b64_e32 v[178:179], v[154:155]
	v_and_b32_e32 v202, 31, v0
	v_bfe_u32 v203, v0, 5, 1
	v_bfe_u32 v204, v0, 6, 1
	v_bfe_u32 v205, v0, 7, 1
	v_bfe_u32 v206, v0, 8, 1
	v_lshrrev_b32_e32 v207, 3, v0
	v_and_b32_e32 v208, 7, v0
	v_lshlrev_b32_e32 v209, 1, v202
	v_lshl_add_u32 v209, v204, 6, v209
	v_add_u32_e32 v209, v209, v205
	v_mul_u32_u24_e32 v209, 0x110, v209
	v_lshl_add_u32 v132, v203, 4, v209
	v_lshl_add_u32 v209, v204, 5, v202
	v_mul_u32_u24_e32 v209, 0x110, v209
	v_lshl_add_u32 v209, v203, 4, v209
	v_mul_u32_u24_e32 v211, 0x4400, v205
	v_add_u32_e32 v156, v209, v211
	v_mul_u32_u24_e32 v209, 0x110, v207
	v_lshl_add_u32 v158, v208, 4, v209
	v_mul_u32_u24_e32 v209, 0x240, v207
	v_lshl_add_u32 v209, v208, 4, v209
	v_add_u32_e32 v174, 0x8800, v209
	v_add_u32_e32 v175, 0xe800, v174
	v_lshl_add_u32 v209, v205, 1, v206
	v_lshl_add_u32 v209, v209, 5, v202
	v_mul_u32_u24_e32 v209, 0x90, v209
	v_lshl_add_u32 v209, v204, 6, v209
	v_lshl_add_u32 v209, v203, 3, v209
	v_add_u32_e32 v176, 0x11800, v209
	v_add_u32_e32 v177, 0xe800, v176
	v_lshl_add_u32 v209, v206, 5, v202
	v_mul_u32_u24_e32 v209, 0x90, v209
	v_lshl_add_u32 v209, v203, 4, v209
	v_add_u32_e32 v180, 0x11800, v209
	v_add_u32_e32 v182, 0xe800, v180
	v_bfe_u32 v210, v0, 2, 2
	v_lshl_add_u32 v210, v203, 3, v210
	v_mul_u32_u24_e32 v210, 0x240, v210
	v_bfe_u32 v211, v0, 6, 2
	v_lshl_add_u32 v210, v211, 7, v210
	v_bfe_u32 v211, v0, 4, 1
	v_lshl_add_u32 v210, v211, 5, v210
	v_and_b32_e32 v211, 3, v0
	v_lshl_add_u32 v210, v211, 3, v210
	v_add_u32_e32 v183, 0x8800, v210
	v_add_u32_e32 v184, 0xe800, v183
	s_add_i32 s16, s87, 1
	s_min_u32 s16, s16, s83
	s_lshl_b32 s16, s16, 6
	v_mad_i64_i32 v[250:251], s[88:89], s16, v166, v[160:161]
	global_load_dwordx4 v[234:237], v[250:251], off
	global_load_dwordx4 v[238:241], v[250:251], off offset:128
	global_load_dwordx4 v[242:245], v[250:251], off offset:256
	global_load_dwordx4 v[246:249], v[250:251], off offset:384
	s_add_i32 s16, s87, 1
	s_min_u32 s16, s16, s83
	s_lshl_b32 s16, s16, 6
	v_mad_i64_i32 v[250:251], s[88:89], s16, v166, v[178:179]
	global_load_dwordx4 v[140:143], v[250:251], off
	global_load_dwordx4 v[144:147], v[250:251], off offset:128
	global_load_dwordx4 v[148:151], v[250:251], off offset:256
	global_load_dwordx4 v[152:155], v[250:251], off offset:384
	s_add_i32 s16, s87, 2
	s_min_u32 s16, s16, s83
	s_lshl_b32 s16, s16, 6
	v_mad_i64_i32 v[250:251], s[88:89], s16, v166, v[160:161]
	global_load_dwordx4 v[186:189], v[250:251], off
	global_load_dwordx4 v[190:193], v[250:251], off offset:128
	global_load_dwordx4 v[194:197], v[250:251], off offset:256
	global_load_dwordx4 v[198:201], v[250:251], off offset:384
	ds_read_b128 v[202:205], v132
	ds_read_b128 v[206:209], v132 offset:32
	ds_read_b128 v[210:213], v132 offset:64
	ds_read_b128 v[214:217], v132 offset:96
	ds_read_b128 v[218:221], v132 offset:128
	ds_read_b128 v[222:225], v132 offset:160
	ds_read_b128 v[226:229], v132 offset:192
	ds_read_b128 v[230:233], v132 offset:224
	ds_write_b128 v174, v[128:131]
	ds_write_b128 v174, v[124:127] offset:128
	ds_write_b128 v174, v[120:123] offset:256
	ds_write_b128 v174, v[116:119] offset:384
	s_waitcnt lgkmcnt(11)
	v_mfma_f32_32x32x16_bf16 v[68:83], v[202:205], v[112:115], 0
	s_waitcnt lgkmcnt(10)
	v_mfma_f32_32x32x16_bf16 v[68:83], v[206:209], v[108:111], v[68:83]
	s_waitcnt lgkmcnt(9)
	v_mfma_f32_32x32x16_bf16 v[68:83], v[210:213], v[104:107], v[68:83]
	s_waitcnt lgkmcnt(8)
	v_mfma_f32_32x32x16_bf16 v[68:83], v[214:217], v[100:103], v[68:83]
	s_waitcnt lgkmcnt(7)
	v_mfma_f32_32x32x16_bf16 v[68:83], v[218:221], v[96:99], v[68:83]
	s_waitcnt lgkmcnt(6)
	v_mfma_f32_32x32x16_bf16 v[68:83], v[222:225], v[92:95], v[68:83]
	s_waitcnt lgkmcnt(5)
	v_mfma_f32_32x32x16_bf16 v[68:83], v[226:229], v[88:91], v[68:83]
	s_waitcnt lgkmcnt(4)
	v_mfma_f32_32x32x16_bf16 v[68:83], v[230:233], v[84:87], v[68:83]
	s_nop 11
	v_sub_f32_e32 v68, v68, v170
	v_sub_f32_e32 v69, v69, v170
	v_sub_f32_e32 v70, v70, v170
	v_sub_f32_e32 v71, v71, v170
	v_sub_f32_e32 v72, v72, v170
	v_sub_f32_e32 v73, v73, v170
	v_sub_f32_e32 v74, v74, v170
	v_sub_f32_e32 v75, v75, v170
	v_sub_f32_e32 v76, v76, v170
	v_sub_f32_e32 v77, v77, v170
	v_sub_f32_e32 v78, v78, v170
	v_sub_f32_e32 v79, v79, v170
	v_sub_f32_e32 v80, v80, v170
	v_sub_f32_e32 v81, v81, v170
	v_sub_f32_e32 v82, v82, v170
	v_sub_f32_e32 v83, v83, v170
	v_exp_f32_e32 v68, v68
	v_exp_f32_e32 v69, v69
	v_exp_f32_e32 v70, v70
	v_exp_f32_e32 v71, v71
	v_exp_f32_e32 v72, v72
	v_exp_f32_e32 v73, v73
	v_exp_f32_e32 v74, v74
	v_exp_f32_e32 v75, v75
	v_exp_f32_e32 v76, v76
	v_exp_f32_e32 v77, v77
	v_exp_f32_e32 v78, v78
	v_exp_f32_e32 v79, v79
	v_exp_f32_e32 v80, v80
	v_exp_f32_e32 v81, v81
	v_exp_f32_e32 v82, v82
	v_exp_f32_e32 v83, v83
	v_cvt_pk_bf16_f32 v132, v68, v69
	v_cvt_pk_bf16_f32 v133, v70, v71
	v_cvt_pk_bf16_f32 v134, v72, v73
	v_cvt_pk_bf16_f32 v135, v74, v75
	v_cvt_pk_bf16_f32 v136, v76, v77
	v_cvt_pk_bf16_f32 v137, v78, v79
	v_cvt_pk_bf16_f32 v138, v80, v81
	v_cvt_pk_bf16_f32 v139, v82, v83
	ds_write2_b64 v176, v[132:133], v[134:135] offset1:2
	ds_write2_b64 v176, v[136:137], v[138:139] offset0:4 offset1:6
	v_add_f32_e32 v181, v181, v68
	v_add_f32_e32 v181, v69, v181
	v_add_f32_e32 v181, v70, v181
	v_add_f32_e32 v181, v71, v181
	v_add_f32_e32 v181, v72, v181
	v_add_f32_e32 v181, v73, v181
	v_add_f32_e32 v181, v74, v181
	v_add_f32_e32 v181, v75, v181
	v_add_f32_e32 v181, v76, v181
	v_add_f32_e32 v181, v77, v181
	v_add_f32_e32 v181, v78, v181
	v_add_f32_e32 v181, v79, v181
	v_add_f32_e32 v181, v80, v181
	v_add_f32_e32 v181, v81, v181
	v_add_f32_e32 v181, v82, v181
	v_add_f32_e32 v181, v83, v181
	s_waitcnt lgkmcnt(0)
	s_barrier
	s_waitcnt vmcnt(8)
	ds_write_b128 v158, v[234:237]
	ds_write_b128 v158, v[238:241] offset:128
	ds_write_b128 v158, v[242:245] offset:17408
	ds_write_b128 v158, v[246:249] offset:17536
	s_add_i32 s16, s87, 2
	s_min_u32 s16, s16, s83
	s_lshl_b32 s16, s16, 6
	v_mad_i64_i32 v[250:251], s[88:89], s16, v166, v[178:179]
	global_load_dwordx4 v[128:131], v[250:251], off
	global_load_dwordx4 v[124:127], v[250:251], off offset:128
	global_load_dwordx4 v[120:123], v[250:251], off offset:256
	global_load_dwordx4 v[116:119], v[250:251], off offset:384
	s_add_i32 s16, s87, 3
	s_min_u32 s16, s16, s83
	s_lshl_b32 s16, s16, 6
	v_mad_i64_i32 v[250:251], s[88:89], s16, v166, v[160:161]
	global_load_dwordx4 v[234:237], v[250:251], off
	global_load_dwordx4 v[238:241], v[250:251], off offset:128
	global_load_dwordx4 v[242:245], v[250:251], off offset:256
	global_load_dwordx4 v[246:249], v[250:251], off offset:384
	s_waitcnt lgkmcnt(0)
	s_barrier
	s_cmp_lt_u32 s87, s83
	s_cbranch_scc0 .Lfa_fin_s1
;     template <bool BG = false>
;     __device__ __forceinline__ void run(LAS unsigned char* lds, f32x16 (&O)[NCOMP][NBLK], BgConv* bg = nullptr) const {
;     ...
;         auto body = [&](const int t, auto moret, auto bgt) {
;             constexpr bool more = decltype(moret)::value, BGI = decltype(bgt)::value;
;             if (more) tile_load(kreg, K + (size_t)(64 * (t + 1)) * ldk, ldk, tid);
;             f32x16 st;
; #pragma unroll
;             for (int i = 0; i < 16; ++i) st[i] = 0.f;
;             if (DH == 128) {
;                 bf16x8 kfa[KS];
; #pragma unroll
;                 for (int s = 0; s < KS; ++s) kfa[s] = *(const LAS bf16x8*)(kbuf + ((32 * kh + r) * NCOMP + compA) * KST + (16 * s + 8 * h) * 2);
;                 asm volatile("" ::: "memory");
;                 tile_store_raw(vreg, vbuf, tid);
; #pragma unroll
;                 for (int s = 0; s < KS; ++s) st = MFMA32(kfa[s], qf[s], st);
;             } else {
;             tile_store_raw(vreg, vbuf, tid);
; #pragma unroll
;             for (int s = 0; s < KS; ++s) { const bf16x8 kf = *(const LAS bf16x8*)(kbuf + ((32 * kh + r) * NCOMP + compA) * KST + (16 * s + 8 * h) * 2); st = MFMA32(kf, qf[s], st);
;                 if ((s & 3) == 3) asm volatile("" ::: "memory"); }
;             }
;             float pe[16];
; #pragma unroll
;             for (int i = 0; i < 16; ++i) { pe[i] = fexp2(st[i] - m2); lsum += pe[i]; }
; #pragma unroll
;             for (int g = 0; g < 4; ++g) { u32x2 w; w.x = pk2(pe[4 * g], pe[4 * g + 1]); w.y = pk2(pe[4 * g + 2], pe[4 * g + 3]);
;                 *(LAS u32x2*)(pbuf + ((compA * NRB + rbA) * 32 + r) * PST + (32 * kh + 8 * g + 4 * h) * 2) = w; }
;             __syncthreads();
;             if (more) tile_load(vreg, V + (size_t)(64 * (t + 1)) * ldv, ldv, tid);
; #pragma unroll
;             for (int s = 0; s < 4; ++s) {
;                 bf16x8 pf[NCOMP];
; #pragma unroll
;                 for (int c = 0; c < NCOMP; ++c) pf[c] = *(const LAS bf16x8*)(pbuf + ((c * NRB + rbB) * 32 + r) * PST + (16 * s + 8 * h) * 2);
; #pragma unroll
;                 for (int b = 0; b < NBLK; ++b) {
;                     const bf16x8 vf = trfrag(vbuf + (16 * s + 8 * h + q4) * VST + (DVW * dvp + 32 * b + 16 * b16 + 4 * p4) * 2, 4 * VST);
; #pragma unroll
;                     for (int c = 0; c < NCOMP; ++c) O[c][b] = MFMA32(pf[c], vf, O[c][b]);
;                 }
.Lfa_loop_s1:
	ds_read_b128 v[202:205], v156
	ds_read_b128 v[206:209], v156 offset:32
	ds_read_b128 v[210:213], v156 offset:64
	ds_read_b128 v[214:217], v156 offset:96
	ds_read_b128 v[218:221], v156 offset:128
	ds_read_b128 v[222:225], v156 offset:160
	ds_read_b128 v[226:229], v156 offset:192
	ds_read_b128 v[230:233], v156 offset:224
	s_waitcnt vmcnt(12)
	ds_write_b128 v175, v[140:143]
	ds_write_b128 v175, v[144:147] offset:128
	ds_write_b128 v175, v[148:151] offset:256
	ds_write_b128 v175, v[152:155] offset:384
	s_add_i32 s16, s87, 3
	s_min_u32 s16, s16, s83
	s_lshl_b32 s16, s16, 6
	v_mad_i64_i32 v[250:251], s[88:89], s16, v166, v[178:179]
	global_load_dwordx4 v[140:143], v[250:251], off
	global_load_dwordx4 v[144:147], v[250:251], off offset:128
	global_load_dwordx4 v[148:151], v[250:251], off offset:256
	global_load_dwordx4 v[152:155], v[250:251], off offset:384
	s_waitcnt lgkmcnt(11)
	v_mfma_f32_32x32x16_bf16 v[68:83], v[202:205], v[112:115], 0
	s_waitcnt lgkmcnt(10)
	v_mfma_f32_32x32x16_bf16 v[68:83], v[206:209], v[108:111], v[68:83]
	s_waitcnt lgkmcnt(9)
	v_mfma_f32_32x32x16_bf16 v[68:83], v[210:213], v[104:107], v[68:83]
	s_waitcnt lgkmcnt(8)
	v_mfma_f32_32x32x16_bf16 v[68:83], v[214:217], v[100:103], v[68:83]
	s_waitcnt lgkmcnt(7)
	v_mfma_f32_32x32x16_bf16 v[68:83], v[218:221], v[96:99], v[68:83]
	s_waitcnt lgkmcnt(6)
	v_mfma_f32_32x32x16_bf16 v[68:83], v[222:225], v[92:95], v[68:83]
	s_waitcnt lgkmcnt(5)
	v_mfma_f32_32x32x16_bf16 v[68:83], v[226:229], v[88:91], v[68:83]
	s_waitcnt lgkmcnt(4)
	v_mfma_f32_32x32x16_bf16 v[68:83], v[230:233], v[84:87], v[68:83]
	s_barrier
	ds_read_b128 v[218:221], v180
	ds_read_b64_tr_b16 v[226:227], v183
	ds_read_b64_tr_b16 v[228:229], v183 offset:2304
	ds_read_b128 v[222:225], v180 offset:9216
	ds_read_b64_tr_b16 v[230:231], v183 offset:64
	ds_read_b64_tr_b16 v[232:233], v183 offset:2368
	ds_read_b128 v[202:205], v180 offset:32
	ds_read_b64_tr_b16 v[210:211], v183 offset:9216
	ds_read_b64_tr_b16 v[212:213], v183 offset:11520
	ds_read_b128 v[206:209], v180 offset:9248
	ds_read_b64_tr_b16 v[214:215], v183 offset:9280
	ds_read_b64_tr_b16 v[216:217], v183 offset:11584
	s_waitcnt lgkmcnt(9)
	v_mfma_f32_32x32x16_bf16 v[52:67], v[218:221], v[226:229], v[52:67]
	v_sub_f32_e32 v68, v68, v170
	v_sub_f32_e32 v69, v69, v170
	v_sub_f32_e32 v70, v70, v170
	v_sub_f32_e32 v71, v71, v170
	s_waitcnt lgkmcnt(8)
	v_mfma_f32_32x32x16_bf16 v[20:35], v[222:225], v[226:229], v[20:35]
	v_sub_f32_e32 v72, v72, v170
	v_sub_f32_e32 v73, v73, v170
	v_sub_f32_e32 v74, v74, v170
	v_sub_f32_e32 v75, v75, v170
	s_waitcnt lgkmcnt(6)
	v_mfma_f32_32x32x16_bf16 v[36:51], v[218:221], v[230:233], v[36:51]
	v_sub_f32_e32 v76, v76, v170
	v_sub_f32_e32 v77, v77, v170
	v_sub_f32_e32 v78, v78, v170
	v_sub_f32_e32 v79, v79, v170
	v_mfma_f32_32x32x16_bf16 v[4:19], v[222:225], v[230:233], v[4:19]
	v_sub_f32_e32 v80, v80, v170
	v_sub_f32_e32 v81, v81, v170
	v_sub_f32_e32 v82, v82, v170
	v_sub_f32_e32 v83, v83, v170
	ds_read_b128 v[218:221], v180 offset:64
	ds_read_b64_tr_b16 v[226:227], v183 offset:18432
	ds_read_b64_tr_b16 v[228:229], v183 offset:20736
	ds_read_b128 v[222:225], v180 offset:9280
	ds_read_b64_tr_b16 v[230:231], v183 offset:18496
	ds_read_b64_tr_b16 v[232:233], v183 offset:20800
	s_waitcnt lgkmcnt(9)
	v_mfma_f32_32x32x16_bf16 v[52:67], v[202:205], v[210:213], v[52:67]
	v_exp_f32_e32 v68, v68
	v_exp_f32_e32 v69, v69
	v_exp_f32_e32 v70, v70
	v_exp_f32_e32 v71, v71
	s_waitcnt lgkmcnt(8)
	v_mfma_f32_32x32x16_bf16 v[20:35], v[206:209], v[210:213], v[20:35]
	v_exp_f32_e32 v72, v72
	v_exp_f32_e32 v73, v73
	v_exp_f32_e32 v74, v74
	v_exp_f32_e32 v75, v75
	s_waitcnt lgkmcnt(6)
	v_mfma_f32_32x32x16_bf16 v[36:51], v[202:205], v[214:217], v[36:51]
	v_exp_f32_e32 v76, v76
	v_exp_f32_e32 v77, v77
	v_exp_f32_e32 v78, v78
	v_exp_f32_e32 v79, v79
	v_mfma_f32_32x32x16_bf16 v[4:19], v[206:209], v[214:217], v[4:19]
	v_exp_f32_e32 v80, v80
	v_exp_f32_e32 v81, v81
	v_exp_f32_e32 v82, v82
	v_exp_f32_e32 v83, v83
	ds_read_b128 v[202:205], v180 offset:96
	ds_read_b64_tr_b16 v[210:211], v183 offset:27648
	ds_read_b64_tr_b16 v[212:213], v183 offset:29952
	ds_read_b128 v[206:209], v180 offset:9312
	ds_read_b64_tr_b16 v[214:215], v183 offset:27712
	ds_read_b64_tr_b16 v[216:217], v183 offset:30016
	s_waitcnt lgkmcnt(9)
	v_mfma_f32_32x32x16_bf16 v[52:67], v[218:221], v[226:229], v[52:67]
	v_cvt_pk_bf16_f32 v132, v68, v69
	v_cvt_pk_bf16_f32 v133, v70, v71
	v_add_f32_e32 v181, v181, v68
	v_add_f32_e32 v181, v69, v181
	s_waitcnt lgkmcnt(8)
	v_mfma_f32_32x32x16_bf16 v[20:35], v[222:225], v[226:229], v[20:35]
	v_cvt_pk_bf16_f32 v134, v72, v73
	v_cvt_pk_bf16_f32 v135, v74, v75
	v_add_f32_e32 v181, v70, v181
	v_add_f32_e32 v181, v71, v181
	s_waitcnt lgkmcnt(6)
	v_mfma_f32_32x32x16_bf16 v[36:51], v[218:221], v[230:233], v[36:51]
	v_cvt_pk_bf16_f32 v136, v76, v77
	v_cvt_pk_bf16_f32 v137, v78, v79
	v_add_f32_e32 v181, v72, v181
	v_add_f32_e32 v181, v73, v181
	v_mfma_f32_32x32x16_bf16 v[4:19], v[222:225], v[230:233], v[4:19]
	v_cvt_pk_bf16_f32 v138, v80, v81
	v_cvt_pk_bf16_f32 v139, v82, v83
	v_add_f32_e32 v181, v74, v181
	v_add_f32_e32 v181, v75, v181
	ds_write2_b64 v177, v[132:133], v[134:135] offset1:2
	ds_write2_b64 v177, v[136:137], v[138:139] offset0:4 offset1:6
	s_waitcnt lgkmcnt(5)
	v_mfma_f32_32x32x16_bf16 v[52:67], v[202:205], v[210:213], v[52:67]
	v_add_f32_e32 v181, v76, v181
	v_add_f32_e32 v181, v77, v181
	s_waitcnt lgkmcnt(4)
	v_mfma_f32_32x32x16_bf16 v[20:35], v[206:209], v[210:213], v[20:35]
	v_add_f32_e32 v181, v78, v181
	v_add_f32_e32 v181, v79, v181
	s_waitcnt lgkmcnt(2)
	v_mfma_f32_32x32x16_bf16 v[36:51], v[202:205], v[214:217], v[36:51]
	v_add_f32_e32 v181, v80, v181
	v_add_f32_e32 v181, v81, v181
	v_mfma_f32_32x32x16_bf16 v[4:19], v[206:209], v[214:217], v[4:19]
	v_add_f32_e32 v181, v82, v181
	v_add_f32_e32 v181, v83, v181
	s_waitcnt vmcnt(12)
	ds_write_b128 v158, v[186:189]
	ds_write_b128 v158, v[190:193] offset:128
	ds_write_b128 v158, v[194:197] offset:17408
	ds_write_b128 v158, v[198:201] offset:17536
	s_add_i32 s16, s87, 4
	s_min_u32 s16, s16, s83
	s_lshl_b32 s16, s16, 6
	v_mad_i64_i32 v[250:251], s[88:89], s16, v166, v[160:161]
	global_load_dwordx4 v[186:189], v[250:251], off
	global_load_dwordx4 v[190:193], v[250:251], off offset:128
	global_load_dwordx4 v[194:197], v[250:251], off offset:256
	global_load_dwordx4 v[198:201], v[250:251], off offset:384
	s_waitcnt lgkmcnt(0)
	s_barrier
;     template <bool BG = false>
;     __device__ __forceinline__ void run(LAS unsigned char* lds, f32x16 (&O)[NCOMP][NBLK], BgConv* bg = nullptr) const {
;     ...
;         auto body = [&](const int t, auto moret, auto bgt) {
;             constexpr bool more = decltype(moret)::value, BGI = decltype(bgt)::value;
;             if (more) tile_load(kreg, K + (size_t)(64 * (t + 1)) * ldk, ldk, tid);
;             f32x16 st;
; #pragma unroll
;             for (int i = 0; i < 16; ++i) st[i] = 0.f;
;             if (DH == 128) {
;                 bf16x8 kfa[KS];
; #pragma unroll
;                 for (int s = 0; s < KS; ++s) kfa[s] = *(const LAS bf16x8*)(kbuf + ((32 * kh + r) * NCOMP + compA) * KST + (16 * s + 8 * h) * 2);
;                 asm volatile("" ::: "memory");
;                 tile_store_raw(vreg, vbuf, tid);
; #pragma unroll
;                 for (int s = 0; s < KS; ++s) st = MFMA32(kfa[s], qf[s], st);
;             } else {
;             tile_store_raw(vreg, vbuf, tid);
; #pragma unroll
;             for (int s = 0; s < KS; ++s) { const bf16x8 kf = *(const LAS bf16x8*)(kbuf + ((32 * kh + r) * NCOMP + compA) * KST + (16 * s + 8 * h) * 2); st = MFMA32(kf, qf[s], st);
;                 if ((s & 3) == 3) asm volatile("" ::: "memory"); }
;             }
;             float pe[16];
; #pragma unroll
;             for (int i = 0; i < 16; ++i) { pe[i] = fexp2(st[i] - m2); lsum += pe[i]; }
; #pragma unroll
;             for (int g = 0; g < 4; ++g) { u32x2 w; w.x = pk2(pe[4 * g], pe[4 * g + 1]); w.y = pk2(pe[4 * g + 2], pe[4 * g + 3]);
;                 *(LAS u32x2*)(pbuf + ((compA * NRB + rbA) * 32 + r) * PST + (32 * kh + 8 * g + 4 * h) * 2) = w; }
;             __syncthreads();
;             if (more) tile_load(vreg, V + (size_t)(64 * (t + 1)) * ldv, ldv, tid);
; #pragma unroll
;             for (int s = 0; s < 4; ++s) {
;                 bf16x8 pf[NCOMP];
; #pragma unroll
;                 for (int c = 0; c < NCOMP; ++c) pf[c] = *(const LAS bf16x8*)(pbuf + ((c * NRB + rbB) * 32 + r) * PST + (16 * s + 8 * h) * 2);
; #pragma unroll
;                 for (int b = 0; b < NBLK; ++b) {
;                     const bf16x8 vf = trfrag(vbuf + (16 * s + 8 * h + q4) * VST + (DVW * dvp + 32 * b + 16 * b16 + 4 * p4) * 2, 4 * VST);
; #pragma unroll
;                     for (int c = 0; c < NCOMP; ++c) O[c][b] = MFMA32(pf[c], vf, O[c][b]);
;                 }
	v_swap_b32 v174, v175
	v_swap_b32 v176, v177
	v_swap_b32 v180, v182
	v_swap_b32 v183, v184
	s_add_i32 s87, s87, 1
	s_cmp_lt_u32 s87, s83
	s_cbranch_scc0 .Lfa_fin_s1
	ds_read_b128 v[202:205], v156
	ds_read_b128 v[206:209], v156 offset:32
	ds_read_b128 v[210:213], v156 offset:64
	ds_read_b128 v[214:217], v156 offset:96
	ds_read_b128 v[218:221], v156 offset:128
	ds_read_b128 v[222:225], v156 offset:160
	ds_read_b128 v[226:229], v156 offset:192
	ds_read_b128 v[230:233], v156 offset:224
	s_waitcnt vmcnt(12)
	ds_write_b128 v175, v[128:131]
	ds_write_b128 v175, v[124:127] offset:128
	ds_write_b128 v175, v[120:123] offset:256
	ds_write_b128 v175, v[116:119] offset:384
	s_add_i32 s16, s87, 3
	s_min_u32 s16, s16, s83
	s_lshl_b32 s16, s16, 6
	v_mad_i64_i32 v[250:251], s[88:89], s16, v166, v[178:179]
	global_load_dwordx4 v[128:131], v[250:251], off
	global_load_dwordx4 v[124:127], v[250:251], off offset:128
	global_load_dwordx4 v[120:123], v[250:251], off offset:256
	global_load_dwordx4 v[116:119], v[250:251], off offset:384
	s_waitcnt lgkmcnt(11)
	v_mfma_f32_32x32x16_bf16 v[68:83], v[202:205], v[112:115], 0
	s_waitcnt lgkmcnt(10)
	v_mfma_f32_32x32x16_bf16 v[68:83], v[206:209], v[108:111], v[68:83]
	s_waitcnt lgkmcnt(9)
	v_mfma_f32_32x32x16_bf16 v[68:83], v[210:213], v[104:107], v[68:83]
	s_waitcnt lgkmcnt(8)
	v_mfma_f32_32x32x16_bf16 v[68:83], v[214:217], v[100:103], v[68:83]
	s_waitcnt lgkmcnt(7)
	v_mfma_f32_32x32x16_bf16 v[68:83], v[218:221], v[96:99], v[68:83]
	s_waitcnt lgkmcnt(6)
	v_mfma_f32_32x32x16_bf16 v[68:83], v[222:225], v[92:95], v[68:83]
	s_waitcnt lgkmcnt(5)
	v_mfma_f32_32x32x16_bf16 v[68:83], v[226:229], v[88:91], v[68:83]
	s_waitcnt lgkmcnt(4)
	v_mfma_f32_32x32x16_bf16 v[68:83], v[230:233], v[84:87], v[68:83]
	s_barrier
	ds_read_b128 v[218:221], v180
	ds_read_b64_tr_b16 v[226:227], v183
	ds_read_b64_tr_b16 v[228:229], v183 offset:2304
	ds_read_b128 v[222:225], v180 offset:9216
	ds_read_b64_tr_b16 v[230:231], v183 offset:64
	ds_read_b64_tr_b16 v[232:233], v183 offset:2368
	ds_read_b128 v[202:205], v180 offset:32
	ds_read_b64_tr_b16 v[210:211], v183 offset:9216
	ds_read_b64_tr_b16 v[212:213], v183 offset:11520
	ds_read_b128 v[206:209], v180 offset:9248
	ds_read_b64_tr_b16 v[214:215], v183 offset:9280
	ds_read_b64_tr_b16 v[216:217], v183 offset:11584
	s_waitcnt lgkmcnt(9)
	v_mfma_f32_32x32x16_bf16 v[52:67], v[218:221], v[226:229], v[52:67]
	v_sub_f32_e32 v68, v68, v170
	v_sub_f32_e32 v69, v69, v170
	v_sub_f32_e32 v70, v70, v170
	v_sub_f32_e32 v71, v71, v170
	s_waitcnt lgkmcnt(8)
	v_mfma_f32_32x32x16_bf16 v[20:35], v[222:225], v[226:229], v[20:35]
	v_sub_f32_e32 v72, v72, v170
	v_sub_f32_e32 v73, v73, v170
	v_sub_f32_e32 v74, v74, v170
	v_sub_f32_e32 v75, v75, v170
	s_waitcnt lgkmcnt(6)
	v_mfma_f32_32x32x16_bf16 v[36:51], v[218:221], v[230:233], v[36:51]
	v_sub_f32_e32 v76, v76, v170
	v_sub_f32_e32 v77, v77, v170
	v_sub_f32_e32 v78, v78, v170
	v_sub_f32_e32 v79, v79, v170
	v_mfma_f32_32x32x16_bf16 v[4:19], v[222:225], v[230:233], v[4:19]
	v_sub_f32_e32 v80, v80, v170
	v_sub_f32_e32 v81, v81, v170
	v_sub_f32_e32 v82, v82, v170
	v_sub_f32_e32 v83, v83, v170
	ds_read_b128 v[218:221], v180 offset:64
	ds_read_b64_tr_b16 v[226:227], v183 offset:18432
	ds_read_b64_tr_b16 v[228:229], v183 offset:20736
	ds_read_b128 v[222:225], v180 offset:9280
	ds_read_b64_tr_b16 v[230:231], v183 offset:18496
	ds_read_b64_tr_b16 v[232:233], v183 offset:20800
	s_waitcnt lgkmcnt(9)
	v_mfma_f32_32x32x16_bf16 v[52:67], v[202:205], v[210:213], v[52:67]
	v_exp_f32_e32 v68, v68
	v_exp_f32_e32 v69, v69
	v_exp_f32_e32 v70, v70
	v_exp_f32_e32 v71, v71
	s_waitcnt lgkmcnt(8)
	v_mfma_f32_32x32x16_bf16 v[20:35], v[206:209], v[210:213], v[20:35]
	v_exp_f32_e32 v72, v72
	v_exp_f32_e32 v73, v73
	v_exp_f32_e32 v74, v74
	v_exp_f32_e32 v75, v75
	s_waitcnt lgkmcnt(6)
	v_mfma_f32_32x32x16_bf16 v[36:51], v[202:205], v[214:217], v[36:51]
	v_exp_f32_e32 v76, v76
	v_exp_f32_e32 v77, v77
	v_exp_f32_e32 v78, v78
	v_exp_f32_e32 v79, v79
	v_mfma_f32_32x32x16_bf16 v[4:19], v[206:209], v[214:217], v[4:19]
	v_exp_f32_e32 v80, v80
	v_exp_f32_e32 v81, v81
	v_exp_f32_e32 v82, v82
	v_exp_f32_e32 v83, v83
	ds_read_b128 v[202:205], v180 offset:96
	ds_read_b64_tr_b16 v[210:211], v183 offset:27648
	ds_read_b64_tr_b16 v[212:213], v183 offset:29952
	ds_read_b128 v[206:209], v180 offset:9312
	ds_read_b64_tr_b16 v[214:215], v183 offset:27712
	ds_read_b64_tr_b16 v[216:217], v183 offset:30016
	s_waitcnt lgkmcnt(9)
	v_mfma_f32_32x32x16_bf16 v[52:67], v[218:221], v[226:229], v[52:67]
	v_cvt_pk_bf16_f32 v132, v68, v69
	v_cvt_pk_bf16_f32 v133, v70, v71
	v_add_f32_e32 v181, v181, v68
	v_add_f32_e32 v181, v69, v181
	s_waitcnt lgkmcnt(8)
	v_mfma_f32_32x32x16_bf16 v[20:35], v[222:225], v[226:229], v[20:35]
	v_cvt_pk_bf16_f32 v134, v72, v73
	v_cvt_pk_bf16_f32 v135, v74, v75
	v_add_f32_e32 v181, v70, v181
	v_add_f32_e32 v181, v71, v181
	s_waitcnt lgkmcnt(6)
	v_mfma_f32_32x32x16_bf16 v[36:51], v[218:221], v[230:233], v[36:51]
	v_cvt_pk_bf16_f32 v136, v76, v77
	v_cvt_pk_bf16_f32 v137, v78, v79
	v_add_f32_e32 v181, v72, v181
	v_add_f32_e32 v181, v73, v181
	v_mfma_f32_32x32x16_bf16 v[4:19], v[222:225], v[230:233], v[4:19]
	v_cvt_pk_bf16_f32 v138, v80, v81
	v_cvt_pk_bf16_f32 v139, v82, v83
	v_add_f32_e32 v181, v74, v181
	v_add_f32_e32 v181, v75, v181
	ds_write2_b64 v177, v[132:133], v[134:135] offset1:2
	ds_write2_b64 v177, v[136:137], v[138:139] offset0:4 offset1:6
	s_waitcnt lgkmcnt(5)
	v_mfma_f32_32x32x16_bf16 v[52:67], v[202:205], v[210:213], v[52:67]
	v_add_f32_e32 v181, v76, v181
	v_add_f32_e32 v181, v77, v181
	s_waitcnt lgkmcnt(4)
	v_mfma_f32_32x32x16_bf16 v[20:35], v[206:209], v[210:213], v[20:35]
	v_add_f32_e32 v181, v78, v181
	v_add_f32_e32 v181, v79, v181
	s_waitcnt lgkmcnt(2)
	v_mfma_f32_32x32x16_bf16 v[36:51], v[202:205], v[214:217], v[36:51]
	v_add_f32_e32 v181, v80, v181
	v_add_f32_e32 v181, v81, v181
	v_mfma_f32_32x32x16_bf16 v[4:19], v[206:209], v[214:217], v[4:19]
	v_add_f32_e32 v181, v82, v181
	v_add_f32_e32 v181, v83, v181
	s_waitcnt vmcnt(12)
	ds_write_b128 v158, v[234:237]
	ds_write_b128 v158, v[238:241] offset:128
	ds_write_b128 v158, v[242:245] offset:17408
	ds_write_b128 v158, v[246:249] offset:17536
	s_add_i32 s16, s87, 4
	s_min_u32 s16, s16, s83
	s_lshl_b32 s16, s16, 6
	v_mad_i64_i32 v[250:251], s[88:89], s16, v166, v[160:161]
	global_load_dwordx4 v[234:237], v[250:251], off
	global_load_dwordx4 v[238:241], v[250:251], off offset:128
	global_load_dwordx4 v[242:245], v[250:251], off offset:256
	global_load_dwordx4 v[246:249], v[250:251], off offset:384
	s_waitcnt lgkmcnt(0)
	s_barrier
	v_swap_b32 v174, v175
	v_swap_b32 v176, v177
	v_swap_b32 v180, v182
	v_swap_b32 v183, v184
	s_add_i32 s87, s87, 1
	s_cmp_lt_u32 s87, s83
	s_cbranch_scc1 .Lfa_loop_s1

;     template <bool BG = false>
;     __device__ __forceinline__ void run(LAS unsigned char* lds, f32x16 (&O)[NCOMP][NBLK], BgConv* bg = nullptr) const {
;     ...
;         auto body = [&](const int t, auto moret, auto bgt) {
;             constexpr bool more = decltype(moret)::value, BGI = decltype(bgt)::value;
;             if (more) tile_load(kreg, K + (size_t)(64 * (t + 1)) * ldk, ldk, tid);
;             f32x16 st;
; #pragma unroll
;             for (int i = 0; i < 16; ++i) st[i] = 0.f;
;             if (DH == 128) {
;                 bf16x8 kfa[KS];
; #pragma unroll
;                 for (int s = 0; s < KS; ++s) kfa[s] = *(const LAS bf16x8*)(kbuf + ((32 * kh + r) * NCOMP + compA) * KST + (16 * s + 8 * h) * 2);
;                 asm volatile("" ::: "memory");
;                 tile_store_raw(vreg, vbuf, tid);
; #pragma unroll
;                 for (int s = 0; s < KS; ++s) st = MFMA32(kfa[s], qf[s], st);
;             } else {
;             tile_store_raw(vreg, vbuf, tid);
; #pragma unroll
;             for (int s = 0; s < KS; ++s) { const bf16x8 kf = *(const LAS bf16x8*)(kbuf + ((32 * kh + r) * NCOMP + compA) * KST + (16 * s + 8 * h) * 2); st = MFMA32(kf, qf[s], st);
;                 if ((s & 3) == 3) asm volatile("" ::: "memory"); }
;             }
;             float pe[16];
; #pragma unroll
;             for (int i = 0; i < 16; ++i) { pe[i] = fexp2(st[i] - m2); lsum += pe[i]; }
; #pragma unroll
;             for (int g = 0; g < 4; ++g) { u32x2 w; w.x = pk2(pe[4 * g], pe[4 * g + 1]); w.y = pk2(pe[4 * g + 2], pe[4 * g + 3]);
;                 *(LAS u32x2*)(pbuf + ((compA * NRB + rbA) * 32 + r) * PST + (32 * kh + 8 * g + 4 * h) * 2) = w; }
;             __syncthreads();
;             if (more) tile_load(vreg, V + (size_t)(64 * (t + 1)) * ldv, ldv, tid);
; #pragma unroll
;             for (int s = 0; s < 4; ++s) {
;                 bf16x8 pf[NCOMP];
; #pragma unroll
;                 for (int c = 0; c < NCOMP; ++c) pf[c] = *(const LAS bf16x8*)(pbuf + ((c * NRB + rbB) * 32 + r) * PST + (16 * s + 8 * h) * 2);
; #pragma unroll
;                 for (int b = 0; b < NBLK; ++b) {
;                     const bf16x8 vf = trfrag(vbuf + (16 * s + 8 * h + q4) * VST + (DVW * dvp + 32 * b + 16 * b16 + 4 * p4) * 2, 4 * VST);
; #pragma unroll
;                     for (int c = 0; c < NCOMP; ++c) O[c][b] = MFMA32(pf[c], vf, O[c][b]);
;                 }
.LBB0_768:
	s_waitcnt vmcnt(0)
	v_mov_b64_e32 v[160:161], v[152:153]
	v_mov_b64_e32 v[178:179], v[154:155]
	v_and_b32_e32 v202, 31, v0
	v_bfe_u32 v203, v0, 5, 1
	v_bfe_u32 v204, v0, 6, 1
	v_bfe_u32 v205, v0, 7, 1
	v_bfe_u32 v206, v0, 8, 1
	v_lshrrev_b32_e32 v207, 3, v0
	v_and_b32_e32 v208, 7, v0
	v_lshlrev_b32_e32 v209, 1, v202
	v_lshl_add_u32 v209, v204, 6, v209
	v_add_u32_e32 v209, v209, v205
	v_mul_u32_u24_e32 v209, 0x110, v209
	v_lshl_add_u32 v132, v203, 4, v209
	v_lshl_add_u32 v209, v204, 5, v202
	v_mul_u32_u24_e32 v209, 0x110, v209
	v_lshl_add_u32 v209, v203, 4, v209
	v_mul_u32_u24_e32 v211, 0x4400, v205
	v_add_u32_e32 v156, v209, v211
	v_mul_u32_u24_e32 v209, 0x110, v207
	v_lshl_add_u32 v158, v208, 4, v209
	v_mul_u32_u24_e32 v209, 0x240, v207
	v_lshl_add_u32 v209, v208, 4, v209
	v_add_u32_e32 v173, 0x8800, v209
	v_add_u32_e32 v175, 0xe800, v173
	v_lshl_add_u32 v209, v205, 1, v206
	v_lshl_add_u32 v209, v209, 5, v202
	v_mul_u32_u24_e32 v209, 0x90, v209
	v_lshl_add_u32 v209, v204, 6, v209
	v_lshl_add_u32 v209, v203, 3, v209
	v_add_u32_e32 v176, 0x11800, v209
	v_add_u32_e32 v177, 0xe800, v176
	v_lshl_add_u32 v209, v206, 5, v202
	v_mul_u32_u24_e32 v209, 0x90, v209
	v_lshl_add_u32 v209, v203, 4, v209
	v_add_u32_e32 v180, 0x11800, v209
	v_add_u32_e32 v181, 0xe800, v180
	v_bfe_u32 v210, v0, 2, 2
	v_lshl_add_u32 v210, v203, 3, v210
	v_mul_u32_u24_e32 v210, 0x240, v210
	v_bfe_u32 v211, v0, 6, 2
	v_lshl_add_u32 v210, v211, 7, v210
	v_bfe_u32 v211, v0, 4, 1
	v_lshl_add_u32 v210, v211, 5, v210
	v_and_b32_e32 v211, 3, v0
	v_lshl_add_u32 v210, v211, 3, v210
	v_add_u32_e32 v183, 0x8800, v210
	v_add_u32_e32 v184, 0xe800, v183
	s_add_i32 s16, s74, 1
	s_min_u32 s16, s16, s73
	s_lshl_b32 s16, s16, 6
	v_mad_i64_i32 v[250:251], s[76:77], s16, v166, v[160:161]
	global_load_dwordx4 v[234:237], v[250:251], off
	global_load_dwordx4 v[238:241], v[250:251], off offset:128
	global_load_dwordx4 v[242:245], v[250:251], off offset:256
	global_load_dwordx4 v[246:249], v[250:251], off offset:384
	s_add_i32 s16, s74, 1
	s_min_u32 s16, s16, s73
	s_lshl_b32 s16, s16, 6
	v_mad_i64_i32 v[250:251], s[76:77], s16, v166, v[178:179]
	global_load_dwordx4 v[140:143], v[250:251], off
	global_load_dwordx4 v[144:147], v[250:251], off offset:128
	global_load_dwordx4 v[148:151], v[250:251], off offset:256
	global_load_dwordx4 v[152:155], v[250:251], off offset:384
	s_add_i32 s16, s74, 2
	s_min_u32 s16, s16, s73
	s_lshl_b32 s16, s16, 6
	v_mad_i64_i32 v[250:251], s[76:77], s16, v166, v[160:161]
	global_load_dwordx4 v[186:189], v[250:251], off
	global_load_dwordx4 v[190:193], v[250:251], off offset:128
	global_load_dwordx4 v[194:197], v[250:251], off offset:256
	global_load_dwordx4 v[198:201], v[250:251], off offset:384
	ds_read_b128 v[202:205], v132
	ds_read_b128 v[206:209], v132 offset:32
	ds_read_b128 v[210:213], v132 offset:64
	ds_read_b128 v[214:217], v132 offset:96
	ds_read_b128 v[218:221], v132 offset:128
	ds_read_b128 v[222:225], v132 offset:160
	ds_read_b128 v[226:229], v132 offset:192
	ds_read_b128 v[230:233], v132 offset:224
	ds_write_b128 v173, v[128:131]
	ds_write_b128 v173, v[124:127] offset:128
	ds_write_b128 v173, v[120:123] offset:256
	ds_write_b128 v173, v[116:119] offset:384
	s_waitcnt lgkmcnt(11)
	v_mfma_f32_32x32x16_bf16 v[68:83], v[202:205], v[112:115], 0
	s_waitcnt lgkmcnt(10)
	v_mfma_f32_32x32x16_bf16 v[68:83], v[206:209], v[108:111], v[68:83]
	s_waitcnt lgkmcnt(9)
	v_mfma_f32_32x32x16_bf16 v[68:83], v[210:213], v[104:107], v[68:83]
	s_waitcnt lgkmcnt(8)
	v_mfma_f32_32x32x16_bf16 v[68:83], v[214:217], v[100:103], v[68:83]
	s_waitcnt lgkmcnt(7)
	v_mfma_f32_32x32x16_bf16 v[68:83], v[218:221], v[96:99], v[68:83]
	s_waitcnt lgkmcnt(6)
	v_mfma_f32_32x32x16_bf16 v[68:83], v[222:225], v[92:95], v[68:83]
	s_waitcnt lgkmcnt(5)
	v_mfma_f32_32x32x16_bf16 v[68:83], v[226:229], v[88:91], v[68:83]
	s_waitcnt lgkmcnt(4)
	v_mfma_f32_32x32x16_bf16 v[68:83], v[230:233], v[84:87], v[68:83]
	s_nop 11
	v_sub_f32_e32 v68, v68, v172
	v_sub_f32_e32 v69, v69, v172
	v_sub_f32_e32 v70, v70, v172
	v_sub_f32_e32 v71, v71, v172
	v_sub_f32_e32 v72, v72, v172
	v_sub_f32_e32 v73, v73, v172
	v_sub_f32_e32 v74, v74, v172
	v_sub_f32_e32 v75, v75, v172
	v_sub_f32_e32 v76, v76, v172
	v_sub_f32_e32 v77, v77, v172
	v_sub_f32_e32 v78, v78, v172
	v_sub_f32_e32 v79, v79, v172
	v_sub_f32_e32 v80, v80, v172
	v_sub_f32_e32 v81, v81, v172
	v_sub_f32_e32 v82, v82, v172
	v_sub_f32_e32 v83, v83, v172
	v_exp_f32_e32 v68, v68
	v_exp_f32_e32 v69, v69
	v_exp_f32_e32 v70, v70
	v_exp_f32_e32 v71, v71
	v_exp_f32_e32 v72, v72
	v_exp_f32_e32 v73, v73
	v_exp_f32_e32 v74, v74
	v_exp_f32_e32 v75, v75
	v_exp_f32_e32 v76, v76
	v_exp_f32_e32 v77, v77
	v_exp_f32_e32 v78, v78
	v_exp_f32_e32 v79, v79
	v_exp_f32_e32 v80, v80
	v_exp_f32_e32 v81, v81
	v_exp_f32_e32 v82, v82
	v_exp_f32_e32 v83, v83
	v_cvt_pk_bf16_f32 v132, v68, v69
	v_cvt_pk_bf16_f32 v133, v70, v71
	v_cvt_pk_bf16_f32 v134, v72, v73
	v_cvt_pk_bf16_f32 v135, v74, v75
	v_cvt_pk_bf16_f32 v136, v76, v77
	v_cvt_pk_bf16_f32 v137, v78, v79
	v_cvt_pk_bf16_f32 v138, v80, v81
	v_cvt_pk_bf16_f32 v139, v82, v83
	ds_write2_b64 v176, v[132:133], v[134:135] offset1:2
	ds_write2_b64 v176, v[136:137], v[138:139] offset0:4 offset1:6
	v_add_f32_e32 v182, v182, v68
	v_add_f32_e32 v182, v69, v182
	v_add_f32_e32 v182, v70, v182
	v_add_f32_e32 v182, v71, v182
	v_add_f32_e32 v182, v72, v182
	v_add_f32_e32 v182, v73, v182
	v_add_f32_e32 v182, v74, v182
	v_add_f32_e32 v182, v75, v182
	v_add_f32_e32 v182, v76, v182
	v_add_f32_e32 v182, v77, v182
	v_add_f32_e32 v182, v78, v182
	v_add_f32_e32 v182, v79, v182
	v_add_f32_e32 v182, v80, v182
	v_add_f32_e32 v182, v81, v182
	v_add_f32_e32 v182, v82, v182
	v_add_f32_e32 v182, v83, v182
	s_waitcnt lgkmcnt(0)
	s_barrier
	s_waitcnt vmcnt(8)
	ds_write_b128 v158, v[234:237]
	ds_write_b128 v158, v[238:241] offset:128
	ds_write_b128 v158, v[242:245] offset:17408
	ds_write_b128 v158, v[246:249] offset:17536
	s_add_i32 s16, s74, 2
	s_min_u32 s16, s16, s73
	s_lshl_b32 s16, s16, 6
	v_mad_i64_i32 v[250:251], s[76:77], s16, v166, v[178:179]
	global_load_dwordx4 v[128:131], v[250:251], off
	global_load_dwordx4 v[124:127], v[250:251], off offset:128
	global_load_dwordx4 v[120:123], v[250:251], off offset:256
	global_load_dwordx4 v[116:119], v[250:251], off offset:384
	s_add_i32 s16, s74, 3
	s_min_u32 s16, s16, s73
	s_lshl_b32 s16, s16, 6
	v_mad_i64_i32 v[250:251], s[76:77], s16, v166, v[160:161]
	global_load_dwordx4 v[234:237], v[250:251], off
	global_load_dwordx4 v[238:241], v[250:251], off offset:128
	global_load_dwordx4 v[242:245], v[250:251], off offset:256
	global_load_dwordx4 v[246:249], v[250:251], off offset:384
	s_waitcnt lgkmcnt(0)
	s_barrier
	s_cmp_lt_u32 s74, s73
	s_cbranch_scc0 .Lfa_fin_s2
;     template <bool BG = false>
;     __device__ __forceinline__ void run(LAS unsigned char* lds, f32x16 (&O)[NCOMP][NBLK], BgConv* bg = nullptr) const {
;     ...
;         auto body = [&](const int t, auto moret, auto bgt) {
;             constexpr bool more = decltype(moret)::value, BGI = decltype(bgt)::value;
;             if (more) tile_load(kreg, K + (size_t)(64 * (t + 1)) * ldk, ldk, tid);
;             f32x16 st;
; #pragma unroll
;             for (int i = 0; i < 16; ++i) st[i] = 0.f;
;             if (DH == 128) {
;                 bf16x8 kfa[KS];
; #pragma unroll
;                 for (int s = 0; s < KS; ++s) kfa[s] = *(const LAS bf16x8*)(kbuf + ((32 * kh + r) * NCOMP + compA) * KST + (16 * s + 8 * h) * 2);
;                 asm volatile("" ::: "memory");
;                 tile_store_raw(vreg, vbuf, tid);
; #pragma unroll
;                 for (int s = 0; s < KS; ++s) st = MFMA32(kfa[s], qf[s], st);
;             } else {
;             tile_store_raw(vreg, vbuf, tid);
; #pragma unroll
;             for (int s = 0; s < KS; ++s) { const bf16x8 kf = *(const LAS bf16x8*)(kbuf + ((32 * kh + r) * NCOMP + compA) * KST + (16 * s + 8 * h) * 2); st = MFMA32(kf, qf[s], st);
;                 if ((s & 3) == 3) asm volatile("" ::: "memory"); }
;             }
;             float pe[16];
; #pragma unroll
;             for (int i = 0; i < 16; ++i) { pe[i] = fexp2(st[i] - m2); lsum += pe[i]; }
; #pragma unroll
;             for (int g = 0; g < 4; ++g) { u32x2 w; w.x = pk2(pe[4 * g], pe[4 * g + 1]); w.y = pk2(pe[4 * g + 2], pe[4 * g + 3]);
;                 *(LAS u32x2*)(pbuf + ((compA * NRB + rbA) * 32 + r) * PST + (32 * kh + 8 * g + 4 * h) * 2) = w; }
;             __syncthreads();
;             if (more) tile_load(vreg, V + (size_t)(64 * (t + 1)) * ldv, ldv, tid);
; #pragma unroll
;             for (int s = 0; s < 4; ++s) {
;                 bf16x8 pf[NCOMP];
; #pragma unroll
;                 for (int c = 0; c < NCOMP; ++c) pf[c] = *(const LAS bf16x8*)(pbuf + ((c * NRB + rbB) * 32 + r) * PST + (16 * s + 8 * h) * 2);
; #pragma unroll
;                 for (int b = 0; b < NBLK; ++b) {
;                     const bf16x8 vf = trfrag(vbuf + (16 * s + 8 * h + q4) * VST + (DVW * dvp + 32 * b + 16 * b16 + 4 * p4) * 2, 4 * VST);
; #pragma unroll
;                     for (int c = 0; c < NCOMP; ++c) O[c][b] = MFMA32(pf[c], vf, O[c][b]);
;                 }
.Lfa_loop_s2:
	ds_read_b128 v[202:205], v156
	ds_read_b128 v[206:209], v156 offset:32
	ds_read_b128 v[210:213], v156 offset:64
	ds_read_b128 v[214:217], v156 offset:96
	ds_read_b128 v[218:221], v156 offset:128
	ds_read_b128 v[222:225], v156 offset:160
	ds_read_b128 v[226:229], v156 offset:192
	ds_read_b128 v[230:233], v156 offset:224
	s_waitcnt vmcnt(12)
	ds_write_b128 v175, v[140:143]
	ds_write_b128 v175, v[144:147] offset:128
	ds_write_b128 v175, v[148:151] offset:256
	ds_write_b128 v175, v[152:155] offset:384
	s_add_i32 s16, s74, 3
	s_min_u32 s16, s16, s73
	s_lshl_b32 s16, s16, 6
	v_mad_i64_i32 v[250:251], s[76:77], s16, v166, v[178:179]
	global_load_dwordx4 v[140:143], v[250:251], off
	global_load_dwordx4 v[144:147], v[250:251], off offset:128
	global_load_dwordx4 v[148:151], v[250:251], off offset:256
	global_load_dwordx4 v[152:155], v[250:251], off offset:384
	s_waitcnt lgkmcnt(11)
	v_mfma_f32_32x32x16_bf16 v[68:83], v[202:205], v[112:115], 0
	s_waitcnt lgkmcnt(10)
	v_mfma_f32_32x32x16_bf16 v[68:83], v[206:209], v[108:111], v[68:83]
	s_waitcnt lgkmcnt(9)
	v_mfma_f32_32x32x16_bf16 v[68:83], v[210:213], v[104:107], v[68:83]
	s_waitcnt lgkmcnt(8)
	v_mfma_f32_32x32x16_bf16 v[68:83], v[214:217], v[100:103], v[68:83]
	s_waitcnt lgkmcnt(7)
	v_mfma_f32_32x32x16_bf16 v[68:83], v[218:221], v[96:99], v[68:83]
	s_waitcnt lgkmcnt(6)
	v_mfma_f32_32x32x16_bf16 v[68:83], v[222:225], v[92:95], v[68:83]
	s_waitcnt lgkmcnt(5)
	v_mfma_f32_32x32x16_bf16 v[68:83], v[226:229], v[88:91], v[68:83]
	s_waitcnt lgkmcnt(4)
	v_mfma_f32_32x32x16_bf16 v[68:83], v[230:233], v[84:87], v[68:83]
	s_barrier
	ds_read_b128 v[218:221], v180
	ds_read_b64_tr_b16 v[226:227], v183
	ds_read_b64_tr_b16 v[228:229], v183 offset:2304
	ds_read_b128 v[222:225], v180 offset:9216
	ds_read_b64_tr_b16 v[230:231], v183 offset:64
	ds_read_b64_tr_b16 v[232:233], v183 offset:2368
	ds_read_b128 v[202:205], v180 offset:32
	ds_read_b64_tr_b16 v[210:211], v183 offset:9216
	ds_read_b64_tr_b16 v[212:213], v183 offset:11520
	ds_read_b128 v[206:209], v180 offset:9248
	ds_read_b64_tr_b16 v[214:215], v183 offset:9280
	ds_read_b64_tr_b16 v[216:217], v183 offset:11584
	s_waitcnt lgkmcnt(9)
	v_mfma_f32_32x32x16_bf16 v[52:67], v[218:221], v[226:229], v[52:67]
	v_sub_f32_e32 v68, v68, v172
	v_sub_f32_e32 v69, v69, v172
	v_sub_f32_e32 v70, v70, v172
	v_sub_f32_e32 v71, v71, v172
	s_waitcnt lgkmcnt(8)
	v_mfma_f32_32x32x16_bf16 v[20:35], v[222:225], v[226:229], v[20:35]
	v_sub_f32_e32 v72, v72, v172
	v_sub_f32_e32 v73, v73, v172
	v_sub_f32_e32 v74, v74, v172
	v_sub_f32_e32 v75, v75, v172
	s_waitcnt lgkmcnt(6)
	v_mfma_f32_32x32x16_bf16 v[36:51], v[218:221], v[230:233], v[36:51]
	v_sub_f32_e32 v76, v76, v172
	v_sub_f32_e32 v77, v77, v172
	v_sub_f32_e32 v78, v78, v172
	v_sub_f32_e32 v79, v79, v172
	v_mfma_f32_32x32x16_bf16 v[4:19], v[222:225], v[230:233], v[4:19]
	v_sub_f32_e32 v80, v80, v172
	v_sub_f32_e32 v81, v81, v172
	v_sub_f32_e32 v82, v82, v172
	v_sub_f32_e32 v83, v83, v172
	ds_read_b128 v[218:221], v180 offset:64
	ds_read_b64_tr_b16 v[226:227], v183 offset:18432
	ds_read_b64_tr_b16 v[228:229], v183 offset:20736
	ds_read_b128 v[222:225], v180 offset:9280
	ds_read_b64_tr_b16 v[230:231], v183 offset:18496
	ds_read_b64_tr_b16 v[232:233], v183 offset:20800
	s_waitcnt lgkmcnt(9)
	v_mfma_f32_32x32x16_bf16 v[52:67], v[202:205], v[210:213], v[52:67]
	v_exp_f32_e32 v68, v68
	v_exp_f32_e32 v69, v69
	v_exp_f32_e32 v70, v70
	v_exp_f32_e32 v71, v71
	s_waitcnt lgkmcnt(8)
	v_mfma_f32_32x32x16_bf16 v[20:35], v[206:209], v[210:213], v[20:35]
	v_exp_f32_e32 v72, v72
	v_exp_f32_e32 v73, v73
	v_exp_f32_e32 v74, v74
	v_exp_f32_e32 v75, v75
	s_waitcnt lgkmcnt(6)
	v_mfma_f32_32x32x16_bf16 v[36:51], v[202:205], v[214:217], v[36:51]
	v_exp_f32_e32 v76, v76
	v_exp_f32_e32 v77, v77
	v_exp_f32_e32 v78, v78
	v_exp_f32_e32 v79, v79
	v_mfma_f32_32x32x16_bf16 v[4:19], v[206:209], v[214:217], v[4:19]
	v_exp_f32_e32 v80, v80
	v_exp_f32_e32 v81, v81
	v_exp_f32_e32 v82, v82
	v_exp_f32_e32 v83, v83
	ds_read_b128 v[202:205], v180 offset:96
	ds_read_b64_tr_b16 v[210:211], v183 offset:27648
	ds_read_b64_tr_b16 v[212:213], v183 offset:29952
	ds_read_b128 v[206:209], v180 offset:9312
	ds_read_b64_tr_b16 v[214:215], v183 offset:27712
	ds_read_b64_tr_b16 v[216:217], v183 offset:30016
	s_waitcnt lgkmcnt(9)
	v_mfma_f32_32x32x16_bf16 v[52:67], v[218:221], v[226:229], v[52:67]
	v_cvt_pk_bf16_f32 v132, v68, v69
	v_cvt_pk_bf16_f32 v133, v70, v71
	v_add_f32_e32 v182, v182, v68
	v_add_f32_e32 v182, v69, v182
	s_waitcnt lgkmcnt(8)
	v_mfma_f32_32x32x16_bf16 v[20:35], v[222:225], v[226:229], v[20:35]
	v_cvt_pk_bf16_f32 v134, v72, v73
	v_cvt_pk_bf16_f32 v135, v74, v75
	v_add_f32_e32 v182, v70, v182
	v_add_f32_e32 v182, v71, v182
	s_waitcnt lgkmcnt(6)
	v_mfma_f32_32x32x16_bf16 v[36:51], v[218:221], v[230:233], v[36:51]
	v_cvt_pk_bf16_f32 v136, v76, v77
	v_cvt_pk_bf16_f32 v137, v78, v79
	v_add_f32_e32 v182, v72, v182
	v_add_f32_e32 v182, v73, v182
	v_mfma_f32_32x32x16_bf16 v[4:19], v[222:225], v[230:233], v[4:19]
	v_cvt_pk_bf16_f32 v138, v80, v81
	v_cvt_pk_bf16_f32 v139, v82, v83
	v_add_f32_e32 v182, v74, v182
	v_add_f32_e32 v182, v75, v182
	ds_write2_b64 v177, v[132:133], v[134:135] offset1:2
	ds_write2_b64 v177, v[136:137], v[138:139] offset0:4 offset1:6
	s_waitcnt lgkmcnt(5)
	v_mfma_f32_32x32x16_bf16 v[52:67], v[202:205], v[210:213], v[52:67]
	v_add_f32_e32 v182, v76, v182
	v_add_f32_e32 v182, v77, v182
	s_waitcnt lgkmcnt(4)
	v_mfma_f32_32x32x16_bf16 v[20:35], v[206:209], v[210:213], v[20:35]
	v_add_f32_e32 v182, v78, v182
	v_add_f32_e32 v182, v79, v182
	s_waitcnt lgkmcnt(2)
	v_mfma_f32_32x32x16_bf16 v[36:51], v[202:205], v[214:217], v[36:51]
	v_add_f32_e32 v182, v80, v182
	v_add_f32_e32 v182, v81, v182
	v_mfma_f32_32x32x16_bf16 v[4:19], v[206:209], v[214:217], v[4:19]
	v_add_f32_e32 v182, v82, v182
	v_add_f32_e32 v182, v83, v182
	s_waitcnt vmcnt(12)
	ds_write_b128 v158, v[186:189]
	ds_write_b128 v158, v[190:193] offset:128
	ds_write_b128 v158, v[194:197] offset:17408
	ds_write_b128 v158, v[198:201] offset:17536
	s_add_i32 s16, s74, 4
	s_min_u32 s16, s16, s73
	s_lshl_b32 s16, s16, 6
	v_mad_i64_i32 v[250:251], s[76:77], s16, v166, v[160:161]
	global_load_dwordx4 v[186:189], v[250:251], off
	global_load_dwordx4 v[190:193], v[250:251], off offset:128
	global_load_dwordx4 v[194:197], v[250:251], off offset:256
	global_load_dwordx4 v[198:201], v[250:251], off offset:384
	s_waitcnt lgkmcnt(0)
	s_barrier
;     template <bool BG = false>
;     __device__ __forceinline__ void run(LAS unsigned char* lds, f32x16 (&O)[NCOMP][NBLK], BgConv* bg = nullptr) const {
;     ...
;         auto body = [&](const int t, auto moret, auto bgt) {
;             constexpr bool more = decltype(moret)::value, BGI = decltype(bgt)::value;
;             if (more) tile_load(kreg, K + (size_t)(64 * (t + 1)) * ldk, ldk, tid);
;             f32x16 st;
; #pragma unroll
;             for (int i = 0; i < 16; ++i) st[i] = 0.f;
;             if (DH == 128) {
;                 bf16x8 kfa[KS];
; #pragma unroll
;                 for (int s = 0; s < KS; ++s) kfa[s] = *(const LAS bf16x8*)(kbuf + ((32 * kh + r) * NCOMP + compA) * KST + (16 * s + 8 * h) * 2);
;                 asm volatile("" ::: "memory");
;                 tile_store_raw(vreg, vbuf, tid);
; #pragma unroll
;                 for (int s = 0; s < KS; ++s) st = MFMA32(kfa[s], qf[s], st);
;             } else {
;             tile_store_raw(vreg, vbuf, tid);
; #pragma unroll
;             for (int s = 0; s < KS; ++s) { const bf16x8 kf = *(const LAS bf16x8*)(kbuf + ((32 * kh + r) * NCOMP + compA) * KST + (16 * s + 8 * h) * 2); st = MFMA32(kf, qf[s], st);
;                 if ((s & 3) == 3) asm volatile("" ::: "memory"); }
;             }
;             float pe[16];
; #pragma unroll
;             for (int i = 0; i < 16; ++i) { pe[i] = fexp2(st[i] - m2); lsum += pe[i]; }
; #pragma unroll
;             for (int g = 0; g < 4; ++g) { u32x2 w; w.x = pk2(pe[4 * g], pe[4 * g + 1]); w.y = pk2(pe[4 * g + 2], pe[4 * g + 3]);
;                 *(LAS u32x2*)(pbuf + ((compA * NRB + rbA) * 32 + r) * PST + (32 * kh + 8 * g + 4 * h) * 2) = w; }
;             __syncthreads();
;             if (more) tile_load(vreg, V + (size_t)(64 * (t + 1)) * ldv, ldv, tid);
; #pragma unroll
;             for (int s = 0; s < 4; ++s) {
;                 bf16x8 pf[NCOMP];
; #pragma unroll
;                 for (int c = 0; c < NCOMP; ++c) pf[c] = *(const LAS bf16x8*)(pbuf + ((c * NRB + rbB) * 32 + r) * PST + (16 * s + 8 * h) * 2);
; #pragma unroll
;                 for (int b = 0; b < NBLK; ++b) {
;                     const bf16x8 vf = trfrag(vbuf + (16 * s + 8 * h + q4) * VST + (DVW * dvp + 32 * b + 16 * b16 + 4 * p4) * 2, 4 * VST);
; #pragma unroll
;                     for (int c = 0; c < NCOMP; ++c) O[c][b] = MFMA32(pf[c], vf, O[c][b]);
;                 }
	v_swap_b32 v173, v175
	v_swap_b32 v176, v177
	v_swap_b32 v180, v181
	v_swap_b32 v183, v184
	s_add_i32 s74, s74, 1
	s_cmp_lt_u32 s74, s73
	s_cbranch_scc0 .Lfa_fin_s2
	ds_read_b128 v[202:205], v156
	ds_read_b128 v[206:209], v156 offset:32
	ds_read_b128 v[210:213], v156 offset:64
	ds_read_b128 v[214:217], v156 offset:96
	ds_read_b128 v[218:221], v156 offset:128
	ds_read_b128 v[222:225], v156 offset:160
	ds_read_b128 v[226:229], v156 offset:192
	ds_read_b128 v[230:233], v156 offset:224
	s_waitcnt vmcnt(12)
	ds_write_b128 v175, v[128:131]
	ds_write_b128 v175, v[124:127] offset:128
	ds_write_b128 v175, v[120:123] offset:256
	ds_write_b128 v175, v[116:119] offset:384
	s_add_i32 s16, s74, 3
	s_min_u32 s16, s16, s73
	s_lshl_b32 s16, s16, 6
	v_mad_i64_i32 v[250:251], s[76:77], s16, v166, v[178:179]
	global_load_dwordx4 v[128:131], v[250:251], off
	global_load_dwordx4 v[124:127], v[250:251], off offset:128
	global_load_dwordx4 v[120:123], v[250:251], off offset:256
	global_load_dwordx4 v[116:119], v[250:251], off offset:384
	s_waitcnt lgkmcnt(11)
	v_mfma_f32_32x32x16_bf16 v[68:83], v[202:205], v[112:115], 0
	s_waitcnt lgkmcnt(10)
	v_mfma_f32_32x32x16_bf16 v[68:83], v[206:209], v[108:111], v[68:83]
	s_waitcnt lgkmcnt(9)
	v_mfma_f32_32x32x16_bf16 v[68:83], v[210:213], v[104:107], v[68:83]
	s_waitcnt lgkmcnt(8)
	v_mfma_f32_32x32x16_bf16 v[68:83], v[214:217], v[100:103], v[68:83]
	s_waitcnt lgkmcnt(7)
	v_mfma_f32_32x32x16_bf16 v[68:83], v[218:221], v[96:99], v[68:83]
	s_waitcnt lgkmcnt(6)
	v_mfma_f32_32x32x16_bf16 v[68:83], v[222:225], v[92:95], v[68:83]
	s_waitcnt lgkmcnt(5)
	v_mfma_f32_32x32x16_bf16 v[68:83], v[226:229], v[88:91], v[68:83]
	s_waitcnt lgkmcnt(4)
	v_mfma_f32_32x32x16_bf16 v[68:83], v[230:233], v[84:87], v[68:83]
	s_barrier
	ds_read_b128 v[218:221], v180
	ds_read_b64_tr_b16 v[226:227], v183
	ds_read_b64_tr_b16 v[228:229], v183 offset:2304
	ds_read_b128 v[222:225], v180 offset:9216
	ds_read_b64_tr_b16 v[230:231], v183 offset:64
	ds_read_b64_tr_b16 v[232:233], v183 offset:2368
	ds_read_b128 v[202:205], v180 offset:32
	ds_read_b64_tr_b16 v[210:211], v183 offset:9216
	ds_read_b64_tr_b16 v[212:213], v183 offset:11520
	ds_read_b128 v[206:209], v180 offset:9248
	ds_read_b64_tr_b16 v[214:215], v183 offset:9280
	ds_read_b64_tr_b16 v[216:217], v183 offset:11584
	s_waitcnt lgkmcnt(9)
	v_mfma_f32_32x32x16_bf16 v[52:67], v[218:221], v[226:229], v[52:67]
	v_sub_f32_e32 v68, v68, v172
	v_sub_f32_e32 v69, v69, v172
	v_sub_f32_e32 v70, v70, v172
	v_sub_f32_e32 v71, v71, v172
	s_waitcnt lgkmcnt(8)
	v_mfma_f32_32x32x16_bf16 v[20:35], v[222:225], v[226:229], v[20:35]
	v_sub_f32_e32 v72, v72, v172
	v_sub_f32_e32 v73, v73, v172
	v_sub_f32_e32 v74, v74, v172
	v_sub_f32_e32 v75, v75, v172
	s_waitcnt lgkmcnt(6)
	v_mfma_f32_32x32x16_bf16 v[36:51], v[218:221], v[230:233], v[36:51]
	v_sub_f32_e32 v76, v76, v172
	v_sub_f32_e32 v77, v77, v172
	v_sub_f32_e32 v78, v78, v172
	v_sub_f32_e32 v79, v79, v172
	v_mfma_f32_32x32x16_bf16 v[4:19], v[222:225], v[230:233], v[4:19]
	v_sub_f32_e32 v80, v80, v172
	v_sub_f32_e32 v81, v81, v172
	v_sub_f32_e32 v82, v82, v172
	v_sub_f32_e32 v83, v83, v172
	ds_read_b128 v[218:221], v180 offset:64
	ds_read_b64_tr_b16 v[226:227], v183 offset:18432
	ds_read_b64_tr_b16 v[228:229], v183 offset:20736
	ds_read_b128 v[222:225], v180 offset:9280
	ds_read_b64_tr_b16 v[230:231], v183 offset:18496
	ds_read_b64_tr_b16 v[232:233], v183 offset:20800
	s_waitcnt lgkmcnt(9)
	v_mfma_f32_32x32x16_bf16 v[52:67], v[202:205], v[210:213], v[52:67]
	v_exp_f32_e32 v68, v68
	v_exp_f32_e32 v69, v69
	v_exp_f32_e32 v70, v70
	v_exp_f32_e32 v71, v71
	s_waitcnt lgkmcnt(8)
	v_mfma_f32_32x32x16_bf16 v[20:35], v[206:209], v[210:213], v[20:35]
	v_exp_f32_e32 v72, v72
	v_exp_f32_e32 v73, v73
	v_exp_f32_e32 v74, v74
	v_exp_f32_e32 v75, v75
	s_waitcnt lgkmcnt(6)
	v_mfma_f32_32x32x16_bf16 v[36:51], v[202:205], v[214:217], v[36:51]
	v_exp_f32_e32 v76, v76
	v_exp_f32_e32 v77, v77
	v_exp_f32_e32 v78, v78
	v_exp_f32_e32 v79, v79
	v_mfma_f32_32x32x16_bf16 v[4:19], v[206:209], v[214:217], v[4:19]
	v_exp_f32_e32 v80, v80
	v_exp_f32_e32 v81, v81
	v_exp_f32_e32 v82, v82
	v_exp_f32_e32 v83, v83
	ds_read_b128 v[202:205], v180 offset:96
	ds_read_b64_tr_b16 v[210:211], v183 offset:27648
	ds_read_b64_tr_b16 v[212:213], v183 offset:29952
	ds_read_b128 v[206:209], v180 offset:9312
	ds_read_b64_tr_b16 v[214:215], v183 offset:27712
	ds_read_b64_tr_b16 v[216:217], v183 offset:30016
	s_waitcnt lgkmcnt(9)
	v_mfma_f32_32x32x16_bf16 v[52:67], v[218:221], v[226:229], v[52:67]
	v_cvt_pk_bf16_f32 v132, v68, v69
	v_cvt_pk_bf16_f32 v133, v70, v71
	v_add_f32_e32 v182, v182, v68
	v_add_f32_e32 v182, v69, v182
	s_waitcnt lgkmcnt(8)
	v_mfma_f32_32x32x16_bf16 v[20:35], v[222:225], v[226:229], v[20:35]
	v_cvt_pk_bf16_f32 v134, v72, v73
	v_cvt_pk_bf16_f32 v135, v74, v75
	v_add_f32_e32 v182, v70, v182
	v_add_f32_e32 v182, v71, v182
	s_waitcnt lgkmcnt(6)
	v_mfma_f32_32x32x16_bf16 v[36:51], v[218:221], v[230:233], v[36:51]
	v_cvt_pk_bf16_f32 v136, v76, v77
	v_cvt_pk_bf16_f32 v137, v78, v79
	v_add_f32_e32 v182, v72, v182
	v_add_f32_e32 v182, v73, v182
	v_mfma_f32_32x32x16_bf16 v[4:19], v[222:225], v[230:233], v[4:19]
	v_cvt_pk_bf16_f32 v138, v80, v81
	v_cvt_pk_bf16_f32 v139, v82, v83
	v_add_f32_e32 v182, v74, v182
	v_add_f32_e32 v182, v75, v182
	ds_write2_b64 v177, v[132:133], v[134:135] offset1:2
	ds_write2_b64 v177, v[136:137], v[138:139] offset0:4 offset1:6
	s_waitcnt lgkmcnt(5)
	v_mfma_f32_32x32x16_bf16 v[52:67], v[202:205], v[210:213], v[52:67]
	v_add_f32_e32 v182, v76, v182
	v_add_f32_e32 v182, v77, v182
	s_waitcnt lgkmcnt(4)
	v_mfma_f32_32x32x16_bf16 v[20:35], v[206:209], v[210:213], v[20:35]
	v_add_f32_e32 v182, v78, v182
	v_add_f32_e32 v182, v79, v182
	s_waitcnt lgkmcnt(2)
	v_mfma_f32_32x32x16_bf16 v[36:51], v[202:205], v[214:217], v[36:51]
	v_add_f32_e32 v182, v80, v182
	v_add_f32_e32 v182, v81, v182
	v_mfma_f32_32x32x16_bf16 v[4:19], v[206:209], v[214:217], v[4:19]
	v_add_f32_e32 v182, v82, v182
	v_add_f32_e32 v182, v83, v182
	s_waitcnt vmcnt(12)
	ds_write_b128 v158, v[234:237]
	ds_write_b128 v158, v[238:241] offset:128
	ds_write_b128 v158, v[242:245] offset:17408
	ds_write_b128 v158, v[246:249] offset:17536
	s_add_i32 s16, s74, 4
	s_min_u32 s16, s16, s73
	s_lshl_b32 s16, s16, 6
	v_mad_i64_i32 v[250:251], s[76:77], s16, v166, v[160:161]
	global_load_dwordx4 v[234:237], v[250:251], off
	global_load_dwordx4 v[238:241], v[250:251], off offset:128
	global_load_dwordx4 v[242:245], v[250:251], off offset:256
	global_load_dwordx4 v[246:249], v[250:251], off offset:384
	s_waitcnt lgkmcnt(0)
	s_barrier
	v_swap_b32 v173, v175
	v_swap_b32 v176, v177
	v_swap_b32 v180, v181
	v_swap_b32 v183, v184
	s_add_i32 s74, s74, 1
	s_cmp_lt_u32 s74, s73
	s_cbranch_scc1 .Lfa_loop_s2
